# P16 V-transpose loop (prefetch next step, batched LDS reads) and P18 diff-combine+subLN loop (software pipelined, DPP reductions) rewritten
# speedup vs baseline: 1.0699x; 1.0048x over previous
; #define LAS __attribute__((address_space(3)))
; template <int NC>
; __device__ __forceinline__ void transpose_tiles(LAS unsigned char* lds, const bf16* src, int pitch, int cbase, int cstride, int nct, bf16* dst, int W, int slen, int nrows, int bid_, int G_, int tid) {
;     ...
;     for (int st = bid_; st < nst; st += G_) {
;         const int rt = st / nsc, sc = st % nsc, r0 = rt * 64, b = r0 / slen, t0 = r0 % slen;
;         { const int tok = tid >> 3, ch = tid & 7; u32x4 v[NC];
; #pragma unroll
;           for (int i = 0; i < NC; ++i) v[i] = *(const u32x4*)(src + (size_t)(r0 + tok) * pitch + cbase + (sc * NC + i) * cstride + ch * 8);
; #pragma unroll
;           for (int i = 0; i < NC; ++i) *(LAS u32x4*)(tl + tok * LS + i * 64 + ch * 8) = v[i]; }
;         __syncthreads();
;         { const int col = tid >> 3, tc = tid & 7;
; #pragma unroll
;           for (int i = 0; i < NC; ++i) { unsigned w[4];
; #pragma unroll
;               for (int k = 0; k < 4; ++k) { const unsigned lo = tl[(tc * 8 + 2 * k) * LS + i * 64 + col], hi = tl[(tc * 8 + 2 * k + 1) * LS + i * 64 + col]; w[k] = lo | (hi << 16); }
;               u32x4 o; o.x = w[0]; o.y = w[1]; o.z = w[2]; o.w = w[3];
;               *(u32x4*)(dst + ((size_t)b * W + (sc * NC + i) * 64 + col) * slen + t0 + tc * 8) = o; } }
;         __syncthreads();
;     }
.LBB0_861:
	v_readlane_b32 s2, v254, 6
	v_readlane_b32 s3, v254, 7
	s_andn2_b64 vcc, exec, s[2:3]
	s_cbranch_vccnz .LBB0_865
	v_readlane_b32 s2, v254, 8
	v_readlane_b32 s3, v254, 9
	v_mov_b32_e32 v0, v212
	s_andn2_b64 vcc, exec, s[2:3]
	s_cbranch_vccnz .LBB0_865
	v_readlane_b32 s2, v252, 18
	v_readlane_b32 s3, v252, 19
	s_load_dword s2, s[2:3], 0x0
	v_and_b32_e32 v8, 7, v0
	v_readlane_b32 s4, v254, 10
	v_ashrrev_i32_e32 v2, 3, v0
	v_lshlrev_b32_e32 v0, 4, v8
	v_readlane_b32 s5, v254, 11
	s_movk_i32 s3, 0x210
	v_mul_lo_u32 v3, v2, s3
	v_lshl_add_u64 v[4:5], s[4:5], 0, v[0:1]
	v_readlane_b32 s4, v252, 24
	v_add_u32_e32 v9, 0, v3
	v_readlane_b32 s5, v252, 25
	v_mul_u32_u24_e32 v8, 0x1080, v8
	s_waitcnt vmcnt(0)
	v_lshlrev_b32_e32 v10, 1, v2
	v_ashrrev_i32_e32 v3, 31, v2
	v_lshl_add_u64 v[6:7], s[4:5], 0, v[0:1]
	v_add3_u32 v8, 0, v8, v10
	s_waitcnt lgkmcnt(0)
	s_lshl_b32 s3, s2, 8
	v_add_u32_e32 v0, v9, v0
	v_readlane_b32 s4, v255, 33
	s_mov_b32 s5, s84
	s_movk_i32 s13, 0x1800
	s_ashr_i32 s6, s5, 31
	s_lshr_b32 s7, s6, 30
	s_add_i32 s7, s5, s7
	s_ashr_i32 s7, s7, 2
	s_lshl_b32 s12, s7, 6
	s_lshl_b32 s8, s7, 10
	s_sub_i32 s8, s4, s8
	s_ashr_i32 s9, s8, 31
	v_add_u32_e32 v9, s12, v2
	v_mad_i64_i32 v[10:11], s[10:11], v9, s13, v[4:5]
	v_lshl_add_u64 v[22:23], s[8:9], 1, v[10:11]
	global_load_dwordx4 v[10:13], v[22:23], off
	global_load_dwordx4 v[14:17], v[22:23], off offset:128
	global_load_dwordx4 v[18:21], v[22:23], off offset:256
	s_nop 0
	global_load_dwordx4 v[22:25], v[22:23], off offset:384
.Lt16_loop:
	s_bfe_i32 s7, s7, 0x10019
	s_lshr_b32 s6, s6, 22
	s_lshr_b32 s7, s7, 18
	s_add_i32 s6, s5, s6
	s_add_i32 s7, s12, s7
	s_ashr_i32 s6, s6, 10
	s_and_b32 s7, s7, 0xffffc000
	s_sub_i32 s10, s12, s7
	s_ashr_i32 s7, s6, 31
	s_lshl_b64 s[6:7], s[6:7], 10
	s_ashr_i32 s11, s10, 31
	v_lshl_add_u64 v[82:83], s[6:7], 0, v[2:3]
	v_lshl_add_u64 v[84:85], s[10:11], 1, v[6:7]
	v_lshl_add_u64 v[58:59], v[82:83], 0, s[8:9]
	v_lshlrev_b64 v[58:59], 15, v[58:59]
	v_lshl_add_u64 v[58:59], v[84:85], 0, v[58:59]
	s_add_i32 s6, s8, 0x40
	s_ashr_i32 s7, s6, 31
	v_lshl_add_u64 v[60:61], v[82:83], 0, s[6:7]
	v_lshlrev_b64 v[60:61], 15, v[60:61]
	v_lshl_add_u64 v[60:61], v[84:85], 0, v[60:61]
	s_add_i32 s6, s8, 0x80
	s_ashr_i32 s7, s6, 31
	v_lshl_add_u64 v[62:63], v[82:83], 0, s[6:7]
	v_lshlrev_b64 v[62:63], 15, v[62:63]
	v_lshl_add_u64 v[62:63], v[84:85], 0, v[62:63]
	s_add_i32 s6, s8, 0xc0
	s_ashr_i32 s7, s6, 31
	v_lshl_add_u64 v[64:65], v[82:83], 0, s[6:7]
	v_lshlrev_b64 v[64:65], 15, v[64:65]
	v_lshl_add_u64 v[64:65], v[84:85], 0, v[64:65]
	s_add_i32 s5, s5, s2
	s_add_i32 s4, s4, s3
	s_waitcnt vmcnt(0)
	ds_write_b128 v0, v[10:13]
	ds_write_b128 v0, v[14:17] offset:128
	ds_write_b128 v0, v[18:21] offset:256
	ds_write_b128 v0, v[22:25] offset:384
	s_cmpk_lt_i32 s5, 0x800
	s_cbranch_scc0 .Lt16_nopf
	s_ashr_i32 s6, s5, 31
	s_lshr_b32 s7, s6, 30
	s_add_i32 s7, s5, s7
	s_ashr_i32 s7, s7, 2
	s_lshl_b32 s12, s7, 6
	s_lshl_b32 s8, s7, 10
	s_sub_i32 s8, s4, s8
	s_ashr_i32 s9, s8, 31
	v_add_u32_e32 v9, s12, v2
	v_mad_i64_i32 v[10:11], s[10:11], v9, s13, v[4:5]
	v_lshl_add_u64 v[22:23], s[8:9], 1, v[10:11]
	global_load_dwordx4 v[10:13], v[22:23], off
	global_load_dwordx4 v[14:17], v[22:23], off offset:128
	global_load_dwordx4 v[18:21], v[22:23], off offset:256
	s_nop 0
	global_load_dwordx4 v[22:25], v[22:23], off offset:384
.Lt16_nopf:
	s_waitcnt lgkmcnt(0)
	s_barrier
	ds_read_u16 v26, v8 offset:0
	ds_read_u16 v27, v8 offset:528
	ds_read_u16 v28, v8 offset:1056
	ds_read_u16 v29, v8 offset:1584
	ds_read_u16 v30, v8 offset:2112
	ds_read_u16 v31, v8 offset:2640
	ds_read_u16 v32, v8 offset:3168
	ds_read_u16 v33, v8 offset:3696
	ds_read_u16 v34, v8 offset:128
	ds_read_u16 v35, v8 offset:656
	ds_read_u16 v36, v8 offset:1184
	ds_read_u16 v37, v8 offset:1712
	ds_read_u16 v38, v8 offset:2240
	ds_read_u16 v39, v8 offset:2768
	ds_read_u16 v40, v8 offset:3296
	ds_read_u16 v41, v8 offset:3824
	ds_read_u16 v42, v8 offset:256
	ds_read_u16 v43, v8 offset:784
	ds_read_u16 v44, v8 offset:1312
	ds_read_u16 v45, v8 offset:1840
	ds_read_u16 v46, v8 offset:2368
	ds_read_u16 v47, v8 offset:2896
	ds_read_u16 v48, v8 offset:3424
	ds_read_u16 v49, v8 offset:3952
	ds_read_u16 v50, v8 offset:384
	ds_read_u16 v51, v8 offset:912
	ds_read_u16 v52, v8 offset:1440
	ds_read_u16 v53, v8 offset:1968
	ds_read_u16 v54, v8 offset:2496
	ds_read_u16 v55, v8 offset:3024
	ds_read_u16 v56, v8 offset:3552
	ds_read_u16 v57, v8 offset:4080
	s_waitcnt lgkmcnt(0)
	v_lshl_or_b32 v100, v27, 16, v26
	v_lshl_or_b32 v101, v29, 16, v28
	v_lshl_or_b32 v102, v31, 16, v30
	v_lshl_or_b32 v103, v33, 16, v32
	v_lshl_or_b32 v104, v35, 16, v34
	v_lshl_or_b32 v105, v37, 16, v36
	v_lshl_or_b32 v106, v39, 16, v38
	v_lshl_or_b32 v107, v41, 16, v40
	v_lshl_or_b32 v108, v43, 16, v42
	v_lshl_or_b32 v109, v45, 16, v44
	v_lshl_or_b32 v110, v47, 16, v46
	v_lshl_or_b32 v111, v49, 16, v48
	v_lshl_or_b32 v112, v51, 16, v50
	v_lshl_or_b32 v113, v53, 16, v52
	v_lshl_or_b32 v114, v55, 16, v54
	v_lshl_or_b32 v115, v57, 16, v56
	global_store_dwordx4 v[58:59], v[100:103], off
	global_store_dwordx4 v[60:61], v[104:107], off
	global_store_dwordx4 v[62:63], v[108:111], off
	global_store_dwordx4 v[64:65], v[112:115], off
	s_barrier
	s_cmpk_lt_i32 s5, 0x800
	s_cbranch_scc1 .Lt16_loop

; #define UNPK8(v, f) do { f[0] = bflo(v.x); f[1] = bfhi(v.x); f[2] = bflo(v.y); f[3] = bfhi(v.y); f[4] = bflo(v.z); f[5] = bfhi(v.z); f[6] = bflo(v.w); f[7] = bfhi(v.w); } while (0)
; #define PACK8(v, f) do { v.x = pk2(f[0], f[1]); v.y = pk2(f[2], f[3]); v.z = pk2(f[4], f[5]); v.w = pk2(f[6], f[7]); } while (0)
; __device__ __forceinline__ float shfl_xor_l(float v, int o, int lane) { return __builtin_bit_cast(float, __builtin_amdgcn_ds_bpermute((lane ^ o) << 2, __builtin_bit_cast(int, v))); }
; #define INP(i) (*(const float* const volatile __attribute__((address_space(4)))*)((const __attribute__((address_space(4))) char*)__builtin_amdgcn_kernarg_segment_ptr() + 8 * (i)))
; #define REP(k) for (int rep_ = 0; rep_ < 1 + (int)((DUPMASK >> (k)) & 1u); ++rep_)
; __global__ void __launch_bounds__(NTHREADS, 2) mega_fwd(Args args) {
;     ...
;             REP(18) if (IN(18)) {
;                 PHASE_IDS;
;                 const float lam = *(const float*)(ws + S_LAM); const float osc = 1.0f - (0.8f - 0.6f * expf(-0.3f));
;                 const float* gsub = INP(19);
;                 for (int it = gw; it < T * 2; it += NGW) {
;                     const size_t off = (size_t)it * 512 + lane * 8;
;                     const u32x4 v1 = *(const u32x4*)((const bf16*)(ws + A_O1) + off), v2 = *(const u32x4*)((const bf16*)(ws + A_O2) + off);
;                     float a[8], b2[8]; UNPK8(v1, a); UNPK8(v2, b2);
;                     float ss = 0.f;
; #pragma unroll
;                     for (int i = 0; i < 8; ++i) { a[i] -= lam * b2[i]; ss += a[i] * a[i]; }
;                     ss += shfl_xor_l(ss, 1, lane); ss += shfl_xor_l(ss, 2, lane); ss += shfl_xor_l(ss, 4, lane); ss += shfl_xor_l(ss, 8, lane);
;                     const float r = (1.0f / sqrtf(ss * (1.f / 128.f) + EPS)) * osc;
;                     const float* g = gsub + (lane & 15) * 8;
; #pragma unroll
;                     for (int i = 0; i < 8; ++i) a[i] *= r * g[i];
;                     u32x4 w; PACK8(w, a); *(u32x4*)((bf16*)(ws + A_DO) + off) = w;
;                 }
.LBB0_1013:
	v_readlane_b32 s2, v254, 20
	v_readlane_b32 s3, v254, 21
	s_andn2_b64 vcc, exec, s[2:3]
	s_cbranch_vccnz .LBB0_1017
	v_mov_b32_e32 v0, v212
	s_load_dwordx2 s[6:7], s[82:83], 0x98
	v_readfirstlane_b32 s2, v0
	s_ashr_i32 s3, s2, 6
	v_readlane_b32 s2, v255, 31
	s_add_i32 s2, s3, s2
	s_cmp_gt_i32 s2, 0xffff
	s_cbranch_scc1 .LBB0_1017
	v_readlane_b32 s4, v252, 20
	v_readlane_b32 s5, v252, 21
	v_and_b32_e32 v6, 63, v0
	v_lshlrev_b32_e32 v0, 5, v0
	v_and_b32_e32 v0, 0x1e0, v0
	v_lshlrev_b32_e32 v3, 2, v6
	s_waitcnt lgkmcnt(0)
	v_lshl_add_u64 v[4:5], s[6:7], 0, v[0:1]
	global_load_dword v2, v1, s[4:5]
	v_readlane_b32 s4, v252, 18
	v_readlane_b32 s5, v252, 19
	s_load_dword s4, s[4:5], 0x0
	s_ashr_i32 s5, s3, 31
	v_lshlrev_b32_e32 v0, 4, v6
	v_xor_b32_e32 v8, 4, v3
	v_xor_b32_e32 v9, 8, v3
	s_waitcnt lgkmcnt(0)
	s_lshl_b32 s8, s4, 3
	v_readlane_b32 s4, v255, 31
	s_add_u32 s4, s4, s3
	v_readlane_b32 s3, v255, 32
	s_addc_u32 s5, s3, s5
	s_lshl_b64 s[4:5], s[4:5], 10
	s_add_u32 s4, s74, s4
	s_addc_u32 s5, s75, s5
	s_ashr_i32 s9, s8, 31
	s_waitcnt vmcnt(0)
	v_xor_b32_e32 v10, 16, v3
	v_xor_b32_e32 v11, 32, v3
	v_lshl_add_u64 v[6:7], s[4:5], 0, v[0:1]
	s_lshl_b64 s[10:11], s[8:9], 10
	v_mov_b32_e32 v3, v2
	global_load_dwordx4 v[24:27], v[4:5], off
	global_load_dwordx4 v[20:23], v[4:5], off offset:16
	s_mov_b64 s[98:99], 0x4000000
	s_mov_b64 s[100:101], 0x8000000
	v_mov_b32_e32 v86, 1.5
	v_mov_b32_e32 v44, v6
	v_mov_b32_e32 v45, v7
	global_load_dwordx4 v[28:31], v[44:45], off
	v_lshl_add_u64 v[82:83], v[44:45], 0, s[98:99]
	global_load_dwordx4 v[32:35], v[82:83], off
	s_waitcnt vmcnt(0)
.Lp18_it0:
	s_add_i32 s2, s2, s8
	s_cmp_lt_i32 s2, 0x10000
	s_cbranch_scc0 .Lp18_last0
	v_lshl_add_u64 v[46:47], v[44:45], 0, s[10:11]
	global_load_dwordx4 v[36:39], v[46:47], off
	v_lshl_add_u64 v[82:83], v[46:47], 0, s[98:99]
	global_load_dwordx4 v[40:43], v[82:83], off
	v_lshlrev_b32_e32 v48, 16, v28
	v_and_b32_e32 v49, 0xffff0000, v28
	v_lshlrev_b32_e32 v56, 16, v32
	v_and_b32_e32 v57, 0xffff0000, v32
	v_lshlrev_b32_e32 v50, 16, v29
	v_and_b32_e32 v51, 0xffff0000, v29
	v_lshlrev_b32_e32 v58, 16, v33
	v_and_b32_e32 v59, 0xffff0000, v33
	v_lshlrev_b32_e32 v52, 16, v30
	v_and_b32_e32 v53, 0xffff0000, v30
	v_lshlrev_b32_e32 v60, 16, v34
	v_and_b32_e32 v61, 0xffff0000, v34
	v_lshlrev_b32_e32 v54, 16, v31
	v_and_b32_e32 v55, 0xffff0000, v31
	v_lshlrev_b32_e32 v62, 16, v35
	v_and_b32_e32 v63, 0xffff0000, v35
	v_fma_f32 v48, -v2, v56, v48
	v_fma_f32 v49, -v2, v57, v49
	v_fma_f32 v50, -v2, v58, v50
	v_fma_f32 v51, -v2, v59, v51
	v_fma_f32 v52, -v2, v60, v52
	v_fma_f32 v53, -v2, v61, v53
	v_fma_f32 v54, -v2, v62, v54
	v_fma_f32 v55, -v2, v63, v55
	v_mul_f32_e32 v64, v48, v48
	v_fmac_f32_e32 v64, v49, v49
	v_fmac_f32_e32 v64, v50, v50
	v_fmac_f32_e32 v64, v51, v51
	v_fmac_f32_e32 v64, v52, v52
	v_fmac_f32_e32 v64, v53, v53
	v_fmac_f32_e32 v64, v54, v54
	v_fmac_f32_e32 v64, v55, v55
	s_nop 1
	v_add_f32_dpp v65, v64, v64 quad_perm:[1,0,3,2] row_mask:0xf bank_mask:0xf
	s_nop 1
	v_add_f32_dpp v64, v65, v65 quad_perm:[2,3,0,1] row_mask:0xf bank_mask:0xf
	s_nop 1
	v_add_f32_dpp v65, v64, v64 row_half_mirror row_mask:0xf bank_mask:0xf
	s_nop 1
	v_add_f32_dpp v64, v65, v65 row_mirror row_mask:0xf bank_mask:0xf
	v_fmamk_f32 v65, v64, 0x3c000000, v214
	v_rsq_f32_e32 v66, v65
	s_nop 0
	v_mul_f32_e32 v67, v65, v66
	v_mul_f32_e32 v67, v67, v66
	v_fma_f32 v67, v67, -0.5, v86
	v_mul_f32_e32 v66, v66, v67
	v_mul_f32_e32 v66, 0x3f24fd5c, v66
	v_mul_f32_e32 v68, v66, v24
	v_mul_f32_e32 v69, v66, v25
	v_mul_f32_e32 v70, v66, v26
	v_mul_f32_e32 v71, v66, v27
	v_mul_f32_e32 v72, v66, v20
	v_mul_f32_e32 v73, v66, v21
	v_mul_f32_e32 v74, v66, v22
	v_mul_f32_e32 v75, v66, v23
	v_mul_f32_e32 v48, v48, v68
	v_mul_f32_e32 v49, v49, v69
	v_mul_f32_e32 v50, v50, v70
	v_mul_f32_e32 v51, v51, v71
	v_mul_f32_e32 v52, v52, v72
	v_mul_f32_e32 v53, v53, v73
	v_mul_f32_e32 v54, v54, v74
	v_mul_f32_e32 v55, v55, v75
	v_cvt_pk_bf16_f32 v76, v48, v49
	v_cvt_pk_bf16_f32 v77, v50, v51
	v_cvt_pk_bf16_f32 v78, v52, v53
	v_cvt_pk_bf16_f32 v79, v54, v55
	v_lshl_add_u64 v[84:85], v[44:45], 0, s[100:101]
	global_store_dwordx4 v[84:85], v[76:79], off
	s_waitcnt vmcnt(1)
.Lp18_it1:
	s_add_i32 s2, s2, s8
	s_cmp_lt_i32 s2, 0x10000
	s_cbranch_scc0 .Lp18_last1
	v_lshl_add_u64 v[44:45], v[46:47], 0, s[10:11]
	global_load_dwordx4 v[28:31], v[44:45], off
	v_lshl_add_u64 v[82:83], v[44:45], 0, s[98:99]
	global_load_dwordx4 v[32:35], v[82:83], off
	v_lshlrev_b32_e32 v48, 16, v36
	v_and_b32_e32 v49, 0xffff0000, v36
	v_lshlrev_b32_e32 v56, 16, v40
	v_and_b32_e32 v57, 0xffff0000, v40
	v_lshlrev_b32_e32 v50, 16, v37
	v_and_b32_e32 v51, 0xffff0000, v37
	v_lshlrev_b32_e32 v58, 16, v41
	v_and_b32_e32 v59, 0xffff0000, v41
	v_lshlrev_b32_e32 v52, 16, v38
	v_and_b32_e32 v53, 0xffff0000, v38
	v_lshlrev_b32_e32 v60, 16, v42
	v_and_b32_e32 v61, 0xffff0000, v42
	v_lshlrev_b32_e32 v54, 16, v39
	v_and_b32_e32 v55, 0xffff0000, v39
	v_lshlrev_b32_e32 v62, 16, v43
	v_and_b32_e32 v63, 0xffff0000, v43
	v_fma_f32 v48, -v2, v56, v48
	v_fma_f32 v49, -v2, v57, v49
	v_fma_f32 v50, -v2, v58, v50
	v_fma_f32 v51, -v2, v59, v51
	v_fma_f32 v52, -v2, v60, v52
	v_fma_f32 v53, -v2, v61, v53
	v_fma_f32 v54, -v2, v62, v54
	v_fma_f32 v55, -v2, v63, v55
	v_mul_f32_e32 v64, v48, v48
	v_fmac_f32_e32 v64, v49, v49
	v_fmac_f32_e32 v64, v50, v50
	v_fmac_f32_e32 v64, v51, v51
	v_fmac_f32_e32 v64, v52, v52
	v_fmac_f32_e32 v64, v53, v53
	v_fmac_f32_e32 v64, v54, v54
	v_fmac_f32_e32 v64, v55, v55
	s_nop 1
	v_add_f32_dpp v65, v64, v64 quad_perm:[1,0,3,2] row_mask:0xf bank_mask:0xf
	s_nop 1
	v_add_f32_dpp v64, v65, v65 quad_perm:[2,3,0,1] row_mask:0xf bank_mask:0xf
	s_nop 1
	v_add_f32_dpp v65, v64, v64 row_half_mirror row_mask:0xf bank_mask:0xf
	s_nop 1
	v_add_f32_dpp v64, v65, v65 row_mirror row_mask:0xf bank_mask:0xf
	v_fmamk_f32 v65, v64, 0x3c000000, v214
	v_rsq_f32_e32 v66, v65
	s_nop 0
	v_mul_f32_e32 v67, v65, v66
	v_mul_f32_e32 v67, v67, v66
	v_fma_f32 v67, v67, -0.5, v86
	v_mul_f32_e32 v66, v66, v67
	v_mul_f32_e32 v66, 0x3f24fd5c, v66
	v_mul_f32_e32 v68, v66, v24
	v_mul_f32_e32 v69, v66, v25
	v_mul_f32_e32 v70, v66, v26
	v_mul_f32_e32 v71, v66, v27
	v_mul_f32_e32 v72, v66, v20
	v_mul_f32_e32 v73, v66, v21
	v_mul_f32_e32 v74, v66, v22
	v_mul_f32_e32 v75, v66, v23
	v_mul_f32_e32 v48, v48, v68
	v_mul_f32_e32 v49, v49, v69
	v_mul_f32_e32 v50, v50, v70
	v_mul_f32_e32 v51, v51, v71
	v_mul_f32_e32 v52, v52, v72
	v_mul_f32_e32 v53, v53, v73
	v_mul_f32_e32 v54, v54, v74
	v_mul_f32_e32 v55, v55, v75
	v_cvt_pk_bf16_f32 v76, v48, v49
	v_cvt_pk_bf16_f32 v77, v50, v51
	v_cvt_pk_bf16_f32 v78, v52, v53
	v_cvt_pk_bf16_f32 v79, v54, v55
	v_lshl_add_u64 v[84:85], v[46:47], 0, s[100:101]
	global_store_dwordx4 v[84:85], v[76:79], off
	s_waitcnt vmcnt(1)
	s_branch .Lp18_it0
; #define UNPK8(v, f) do { f[0] = bflo(v.x); f[1] = bfhi(v.x); f[2] = bflo(v.y); f[3] = bfhi(v.y); f[4] = bflo(v.z); f[5] = bfhi(v.z); f[6] = bflo(v.w); f[7] = bfhi(v.w); } while (0)
; #define PACK8(v, f) do { v.x = pk2(f[0], f[1]); v.y = pk2(f[2], f[3]); v.z = pk2(f[4], f[5]); v.w = pk2(f[6], f[7]); } while (0)
; __device__ __forceinline__ float shfl_xor_l(float v, int o, int lane) { return __builtin_bit_cast(float, __builtin_amdgcn_ds_bpermute((lane ^ o) << 2, __builtin_bit_cast(int, v))); }
; __global__ void __launch_bounds__(NTHREADS, 2) mega_fwd(Args args) {
;     ...
;                 for (int it = gw; it < T * 2; it += NGW) {
;                     const size_t off = (size_t)it * 512 + lane * 8;
;                     const u32x4 v1 = *(const u32x4*)((const bf16*)(ws + A_O1) + off), v2 = *(const u32x4*)((const bf16*)(ws + A_O2) + off);
;                     float a[8], b2[8]; UNPK8(v1, a); UNPK8(v2, b2);
;                     float ss = 0.f;
; #pragma unroll
;                     for (int i = 0; i < 8; ++i) { a[i] -= lam * b2[i]; ss += a[i] * a[i]; }
;                     ss += shfl_xor_l(ss, 1, lane); ss += shfl_xor_l(ss, 2, lane); ss += shfl_xor_l(ss, 4, lane); ss += shfl_xor_l(ss, 8, lane);
;                     const float r = (1.0f / sqrtf(ss * (1.f / 128.f) + EPS)) * osc;
;                     const float* g = gsub + (lane & 15) * 8;
; #pragma unroll
;                     for (int i = 0; i < 8; ++i) a[i] *= r * g[i];
;                     u32x4 w; PACK8(w, a); *(u32x4*)((bf16*)(ws + A_DO) + off) = w;
.Lp18_last0:
	v_lshlrev_b32_e32 v48, 16, v28
	v_and_b32_e32 v49, 0xffff0000, v28
	v_lshlrev_b32_e32 v56, 16, v32
	v_and_b32_e32 v57, 0xffff0000, v32
	v_lshlrev_b32_e32 v50, 16, v29
	v_and_b32_e32 v51, 0xffff0000, v29
	v_lshlrev_b32_e32 v58, 16, v33
	v_and_b32_e32 v59, 0xffff0000, v33
	v_lshlrev_b32_e32 v52, 16, v30
	v_and_b32_e32 v53, 0xffff0000, v30
	v_lshlrev_b32_e32 v60, 16, v34
	v_and_b32_e32 v61, 0xffff0000, v34
	v_lshlrev_b32_e32 v54, 16, v31
	v_and_b32_e32 v55, 0xffff0000, v31
	v_lshlrev_b32_e32 v62, 16, v35
	v_and_b32_e32 v63, 0xffff0000, v35
	v_fma_f32 v48, -v2, v56, v48
	v_fma_f32 v49, -v2, v57, v49
	v_fma_f32 v50, -v2, v58, v50
	v_fma_f32 v51, -v2, v59, v51
	v_fma_f32 v52, -v2, v60, v52
	v_fma_f32 v53, -v2, v61, v53
	v_fma_f32 v54, -v2, v62, v54
	v_fma_f32 v55, -v2, v63, v55
	v_mul_f32_e32 v64, v48, v48
	v_fmac_f32_e32 v64, v49, v49
	v_fmac_f32_e32 v64, v50, v50
	v_fmac_f32_e32 v64, v51, v51
	v_fmac_f32_e32 v64, v52, v52
	v_fmac_f32_e32 v64, v53, v53
	v_fmac_f32_e32 v64, v54, v54
	v_fmac_f32_e32 v64, v55, v55
	s_nop 1
	v_add_f32_dpp v65, v64, v64 quad_perm:[1,0,3,2] row_mask:0xf bank_mask:0xf
	s_nop 1
	v_add_f32_dpp v64, v65, v65 quad_perm:[2,3,0,1] row_mask:0xf bank_mask:0xf
	s_nop 1
	v_add_f32_dpp v65, v64, v64 row_half_mirror row_mask:0xf bank_mask:0xf
	s_nop 1
	v_add_f32_dpp v64, v65, v65 row_mirror row_mask:0xf bank_mask:0xf
	v_fmamk_f32 v65, v64, 0x3c000000, v214
	v_rsq_f32_e32 v66, v65
	s_nop 0
	v_mul_f32_e32 v67, v65, v66
	v_mul_f32_e32 v67, v67, v66
	v_fma_f32 v67, v67, -0.5, v86
	v_mul_f32_e32 v66, v66, v67
	v_mul_f32_e32 v66, 0x3f24fd5c, v66
	v_mul_f32_e32 v68, v66, v24
	v_mul_f32_e32 v69, v66, v25
	v_mul_f32_e32 v70, v66, v26
	v_mul_f32_e32 v71, v66, v27
	v_mul_f32_e32 v72, v66, v20
	v_mul_f32_e32 v73, v66, v21
	v_mul_f32_e32 v74, v66, v22
	v_mul_f32_e32 v75, v66, v23
	v_mul_f32_e32 v48, v48, v68
	v_mul_f32_e32 v49, v49, v69
	v_mul_f32_e32 v50, v50, v70
	v_mul_f32_e32 v51, v51, v71
	v_mul_f32_e32 v52, v52, v72
	v_mul_f32_e32 v53, v53, v73
	v_mul_f32_e32 v54, v54, v74
	v_mul_f32_e32 v55, v55, v75
	v_cvt_pk_bf16_f32 v76, v48, v49
	v_cvt_pk_bf16_f32 v77, v50, v51
	v_cvt_pk_bf16_f32 v78, v52, v53
	v_cvt_pk_bf16_f32 v79, v54, v55
	v_lshl_add_u64 v[84:85], v[44:45], 0, s[100:101]
	global_store_dwordx4 v[84:85], v[76:79], off
	s_branch .LBB0_1017
.Lp18_last1:
	v_lshlrev_b32_e32 v48, 16, v36
	v_and_b32_e32 v49, 0xffff0000, v36
	v_lshlrev_b32_e32 v56, 16, v40
	v_and_b32_e32 v57, 0xffff0000, v40
	v_lshlrev_b32_e32 v50, 16, v37
	v_and_b32_e32 v51, 0xffff0000, v37
	v_lshlrev_b32_e32 v58, 16, v41
	v_and_b32_e32 v59, 0xffff0000, v41
	v_lshlrev_b32_e32 v52, 16, v38
	v_and_b32_e32 v53, 0xffff0000, v38
	v_lshlrev_b32_e32 v60, 16, v42
	v_and_b32_e32 v61, 0xffff0000, v42
	v_lshlrev_b32_e32 v54, 16, v39
	v_and_b32_e32 v55, 0xffff0000, v39
	v_lshlrev_b32_e32 v62, 16, v43
	v_and_b32_e32 v63, 0xffff0000, v43
	v_fma_f32 v48, -v2, v56, v48
	v_fma_f32 v49, -v2, v57, v49
	v_fma_f32 v50, -v2, v58, v50
	v_fma_f32 v51, -v2, v59, v51
	v_fma_f32 v52, -v2, v60, v52
	v_fma_f32 v53, -v2, v61, v53
	v_fma_f32 v54, -v2, v62, v54
	v_fma_f32 v55, -v2, v63, v55
	v_mul_f32_e32 v64, v48, v48
	v_fmac_f32_e32 v64, v49, v49
	v_fmac_f32_e32 v64, v50, v50
	v_fmac_f32_e32 v64, v51, v51
	v_fmac_f32_e32 v64, v52, v52
	v_fmac_f32_e32 v64, v53, v53
	v_fmac_f32_e32 v64, v54, v54
	v_fmac_f32_e32 v64, v55, v55
	s_nop 1
	v_add_f32_dpp v65, v64, v64 quad_perm:[1,0,3,2] row_mask:0xf bank_mask:0xf
	s_nop 1
	v_add_f32_dpp v64, v65, v65 quad_perm:[2,3,0,1] row_mask:0xf bank_mask:0xf
	s_nop 1
	v_add_f32_dpp v65, v64, v64 row_half_mirror row_mask:0xf bank_mask:0xf
	s_nop 1
	v_add_f32_dpp v64, v65, v65 row_mirror row_mask:0xf bank_mask:0xf
	v_fmamk_f32 v65, v64, 0x3c000000, v214
	v_rsq_f32_e32 v66, v65
	s_nop 0
	v_mul_f32_e32 v67, v65, v66
	v_mul_f32_e32 v67, v67, v66
	v_fma_f32 v67, v67, -0.5, v86
	v_mul_f32_e32 v66, v66, v67
	v_mul_f32_e32 v66, 0x3f24fd5c, v66
	v_mul_f32_e32 v68, v66, v24
	v_mul_f32_e32 v69, v66, v25
	v_mul_f32_e32 v70, v66, v26
	v_mul_f32_e32 v71, v66, v27
	v_mul_f32_e32 v72, v66, v20
	v_mul_f32_e32 v73, v66, v21
	v_mul_f32_e32 v74, v66, v22
	v_mul_f32_e32 v75, v66, v23
	v_mul_f32_e32 v48, v48, v68
	v_mul_f32_e32 v49, v49, v69
	v_mul_f32_e32 v50, v50, v70
	v_mul_f32_e32 v51, v51, v71
	v_mul_f32_e32 v52, v52, v72
	v_mul_f32_e32 v53, v53, v73
	v_mul_f32_e32 v54, v54, v74
	v_mul_f32_e32 v55, v55, v75
	v_cvt_pk_bf16_f32 v76, v48, v49
	v_cvt_pk_bf16_f32 v77, v50, v51
	v_cvt_pk_bf16_f32 v78, v52, v53
	v_cvt_pk_bf16_f32 v79, v54, v55
	v_lshl_add_u64 v[84:85], v[46:47], 0, s[100:101]
	global_store_dwordx4 v[84:85], v[76:79], off
	s_branch .LBB0_1017
